# P1 prologue sample_rstd loads of all four rows issued together; final layer skips the trailing grid barrier
# speedup vs baseline: 1.0047x; 1.0042x over previous
.LBB0_246:
	v_mov_b32_e32 v2, v0
	s_waitcnt vmcnt(0)
	s_waitcnt lgkmcnt(0)
	s_barrier
	s_mov_b64 s[0:1], 0x4000000
	v_and_b32_e32 v44, 63, v2
	v_ashrrev_i32_e32 v10, 4, v2
	v_and_b32_e32 v6, -4, v10
	v_lshlrev_b32_e32 v2, 4, v44
	v_lshl_add_u64 v[4:5], s[14:15], 0, v[2:3]
	v_ashrrev_i32_e32 v7, 31, v6
	v_lshl_add_u64 v[4:5], v[4:5], 0, s[0:1]
	v_lshlrev_b64 v[8:9], 13, v[6:7]
	v_lshl_add_u64 v[8:9], v[4:5], 0, v[8:9]
	global_load_dwordx4 v[12:15], v[8:9], off
	global_load_dwordx4 v[16:19], v[8:9], off offset:1024
	global_load_dwordx4 v[20:23], v[8:9], off offset:2048
	global_load_dwordx4 v[24:27], v[8:9], off offset:3072
	s_movk_i32 s0, 0x1000
	v_add_co_u32_e32 v8, vcc, s0, v8
	s_add_u32 s8, s12, 0x31c83d00
	s_nop 0
	v_addc_co_u32_e32 v9, vcc, 0, v9, vcc
	global_load_dwordx4 v[28:31], v[8:9], off
	global_load_dwordx4 v[32:35], v[8:9], off offset:1024
	global_load_dwordx4 v[36:39], v[8:9], off offset:2048
	global_load_dwordx4 v[40:43], v[8:9], off offset:3072
	s_mov_b64 s[4:5], 0x1000
	v_lshl_add_u64 v[48:49], v[8:9], 0, s[4:5]
	global_load_dwordx4 v[52:55], v[48:49], off
	global_load_dwordx4 v[56:59], v[48:49], off offset:1024
	global_load_dwordx4 v[60:63], v[48:49], off offset:2048
	global_load_dwordx4 v[64:67], v[48:49], off offset:3072
	v_lshl_add_u64 v[50:51], v[48:49], 0, s[4:5]
	global_load_dwordx4 v[68:71], v[50:51], off
	global_load_dwordx4 v[72:75], v[50:51], off offset:1024
	global_load_dwordx4 v[76:79], v[50:51], off offset:2048
	global_load_dwordx4 v[80:83], v[50:51], off offset:3072
	v_lshl_add_u64 v[48:49], v[50:51], 0, s[4:5]
	global_load_dwordx4 v[84:87], v[48:49], off
	global_load_dwordx4 v[88:91], v[48:49], off offset:1024
	global_load_dwordx4 v[92:95], v[48:49], off offset:2048
	global_load_dwordx4 v[96:99], v[48:49], off offset:3072
	v_lshl_add_u64 v[50:51], v[48:49], 0, s[4:5]
	global_load_dwordx4 v[100:103], v[50:51], off
	global_load_dwordx4 v[104:107], v[50:51], off offset:1024
	global_load_dwordx4 v[108:111], v[50:51], off offset:2048
	global_load_dwordx4 v[112:115], v[50:51], off offset:3072
	v_lshl_add_u64 v[48:49], v[50:51], 0, s[4:5]
	global_load_dwordx4 v[116:119], v[48:49], off
	global_load_dwordx4 v[120:123], v[48:49], off offset:1024
	global_load_dwordx4 v[124:127], v[48:49], off offset:2048
	global_load_dwordx4 v[128:131], v[48:49], off offset:3072
	v_lshl_add_u64 v[50:51], v[48:49], 0, s[4:5]
	global_load_dwordx4 v[132:135], v[50:51], off
	global_load_dwordx4 v[136:139], v[50:51], off offset:1024
	global_load_dwordx4 v[140:143], v[50:51], off offset:2048
	global_load_dwordx4 v[144:147], v[50:51], off offset:3072
	v_lshlrev_b32_e32 v8, 2, v44
	v_xor_b32_e32 v2, 4, v8
	s_addc_u32 s9, s13, 0
	v_cmp_eq_u32_e64 s[0:1], 0, v44
	s_waitcnt vmcnt(0)
	v_mul_f32_e32 v9, v13, v13
	v_mul_f32_e32 v11, v15, v15
	v_mul_f32_e32 v13, v17, v17
	v_mul_f32_e32 v15, v19, v19
	v_mul_f32_e32 v17, v21, v21
	v_mul_f32_e32 v19, v23, v23
	v_fmac_f32_e32 v9, v12, v12
	v_fmac_f32_e32 v11, v14, v14
	v_fmac_f32_e32 v13, v16, v16
	v_fmac_f32_e32 v15, v18, v18
	v_mul_f32_e32 v21, v25, v25
	v_mul_f32_e32 v23, v27, v27
	v_fmac_f32_e32 v17, v20, v20
	v_fmac_f32_e32 v19, v22, v22
	v_add_f32_e32 v9, v9, v11
	v_add_f32_e32 v11, v13, v15
	v_fmac_f32_e32 v21, v24, v24
	v_fmac_f32_e32 v23, v26, v26
	v_mul_f32_e32 v12, v29, v29
	v_mul_f32_e32 v14, v31, v31
	v_add_f32_e32 v13, v17, v19
	v_add_f32_e32 v9, v9, v11
	v_mul_f32_e32 v16, v33, v33
	v_mul_f32_e32 v18, v35, v35
	v_add_f32_e32 v15, v21, v23
	v_fmac_f32_e32 v12, v28, v28
	v_fmac_f32_e32 v14, v30, v30
	v_add_f32_e32 v9, v9, v13
	v_mul_f32_e32 v20, v37, v37
	v_mul_f32_e32 v22, v39, v39
	v_fmac_f32_e32 v16, v32, v32
	v_fmac_f32_e32 v18, v34, v34
	v_add_f32_e32 v11, v12, v14
	v_add_f32_e32 v9, v9, v15
	v_mul_f32_e32 v24, v41, v41
	v_mul_f32_e32 v25, v43, v43
	v_fmac_f32_e32 v20, v36, v36
	v_fmac_f32_e32 v22, v38, v38
	v_add_f32_e32 v12, v16, v18
	v_add_f32_e32 v9, v9, v11
	v_fmac_f32_e32 v24, v40, v40
	v_fmac_f32_e32 v25, v42, v42
	v_add_f32_e32 v14, v20, v22
	v_add_f32_e32 v9, v9, v12
	v_add_f32_e32 v9, v9, v14
	v_add_f32_e32 v11, v24, v25
	v_add_f32_e32 v9, v9, v11
	ds_bpermute_b32 v12, v2, v9
	v_xor_b32_e32 v11, 8, v8
	s_waitcnt lgkmcnt(0)
	v_add_f32_e32 v9, v9, v12
	ds_bpermute_b32 v13, v11, v9
	v_xor_b32_e32 v12, 16, v8
	s_waitcnt lgkmcnt(0)
	v_add_f32_e32 v9, v9, v13
	ds_bpermute_b32 v14, v12, v9
	v_xor_b32_e32 v13, 32, v8
	s_waitcnt lgkmcnt(0)
	v_add_f32_e32 v9, v9, v14
	ds_bpermute_b32 v15, v13, v9
	v_xor_b32_e32 v14, 64, v8
	s_waitcnt lgkmcnt(0)
	v_add_f32_e32 v9, v9, v15
	ds_bpermute_b32 v16, v14, v9
	v_xor_b32_e32 v15, 0x80, v8
	s_waitcnt lgkmcnt(0)
	v_add_f32_e32 v8, v9, v16
	ds_bpermute_b32 v9, v15, v8
	s_and_saveexec_b64 s[6:7], s[0:1]
	s_cbranch_execz .LBB0_248
	s_waitcnt lgkmcnt(0)
	v_add_f32_e32 v8, v8, v9
	v_fmamk_f32 v8, v8, 0x3a000000, v214
	v_mul_f32_e32 v9, 0x4f800000, v8
	v_cmp_gt_f32_e32 vcc, s79, v8
	s_nop 1
	v_cndmask_b32_e32 v8, v8, v9, vcc
	v_sqrt_f32_e32 v9, v8
	s_nop 0
	v_add_u32_e32 v16, -1, v9
	v_fma_f32 v18, -v16, v9, v8
	v_add_u32_e32 v17, 1, v9
	v_cmp_ge_f32_e64 s[4:5], 0, v18
	s_nop 1
	v_cndmask_b32_e64 v16, v9, v16, s[4:5]
	v_fma_f32 v9, -v17, v9, v8
	v_cmp_lt_f32_e64 s[4:5], 0, v9
	s_nop 1
	v_cndmask_b32_e64 v9, v16, v17, s[4:5]
	v_mul_f32_e32 v16, 0x37800000, v9
	v_cndmask_b32_e32 v9, v9, v16, vcc
	v_cmp_class_f32_e32 vcc, v8, v1
	s_nop 1
	v_cndmask_b32_e32 v8, v9, v8, vcc
	v_div_scale_f32 v9, s[4:5], v8, v8, 1.0
	v_rcp_f32_e32 v16, v9
	s_nop 0
	v_fma_f32 v17, -v9, v16, 1.0
	v_fmac_f32_e32 v16, v17, v16
	v_div_scale_f32 v17, vcc, 1.0, v8, 1.0
	v_mul_f32_e32 v18, v17, v16
	v_fma_f32 v19, -v9, v18, v17
	v_fmac_f32_e32 v18, v19, v16
	v_fma_f32 v9, -v9, v18, v17
	v_div_fmas_f32 v9, v9, v16, v18
	v_div_fixup_f32 v16, v9, v8, 1.0
	v_lshl_add_u64 v[8:9], v[6:7], 2, s[8:9]
	flat_store_dword v[8:9], v16
.LBB0_248:
	s_or_b64 exec, exec, s[6:7]
	v_or_b32_e32 v8, 1, v6
	s_waitcnt lgkmcnt(0)
	v_ashrrev_i32_e32 v9, 31, v8
	s_movk_i32 s4, 0x1000
	v_mul_f32_e32 v7, v53, v53
	s_nop 0
	v_mul_f32_e32 v53, v55, v55
	v_mul_f32_e32 v55, v57, v57
	v_mul_f32_e32 v57, v59, v59
	v_mul_f32_e32 v59, v61, v61
	v_mul_f32_e32 v61, v63, v63
	v_fmac_f32_e32 v7, v52, v52
	v_fmac_f32_e32 v53, v54, v54
	v_fmac_f32_e32 v55, v56, v56
	v_fmac_f32_e32 v57, v58, v58
	v_mul_f32_e32 v63, v65, v65
	v_mul_f32_e32 v65, v67, v67
	v_fmac_f32_e32 v59, v60, v60
	v_fmac_f32_e32 v61, v62, v62
	v_add_f32_e32 v7, v7, v53
	v_add_f32_e32 v53, v55, v57
	v_fmac_f32_e32 v63, v64, v64
	v_fmac_f32_e32 v65, v66, v66
	v_add_f32_e32 v55, v59, v61
	v_add_f32_e32 v7, v7, v53
	v_add_f32_e32 v57, v63, v65
	v_add_f32_e32 v7, v7, v55
	v_add_f32_e32 v7, v7, v57
	v_mul_f32_e32 v52, v69, v69
	v_mul_f32_e32 v54, v71, v71
	v_mul_f32_e32 v56, v73, v73
	v_mul_f32_e32 v58, v75, v75
	v_fmac_f32_e32 v52, v68, v68
	v_fmac_f32_e32 v54, v70, v70
	v_mul_f32_e32 v60, v77, v77
	v_mul_f32_e32 v62, v79, v79
	v_fmac_f32_e32 v56, v72, v72
	v_fmac_f32_e32 v58, v74, v74
	v_add_f32_e32 v52, v52, v54
	v_mul_f32_e32 v64, v81, v81
	v_mul_f32_e32 v66, v83, v83
	v_fmac_f32_e32 v60, v76, v76
	v_fmac_f32_e32 v62, v78, v78
	v_add_f32_e32 v53, v56, v58
	v_add_f32_e32 v7, v7, v52
	v_fmac_f32_e32 v64, v80, v80
	v_fmac_f32_e32 v66, v82, v82
	v_add_f32_e32 v54, v60, v62
	v_add_f32_e32 v7, v7, v53
	v_add_f32_e32 v7, v7, v54
	v_add_f32_e32 v52, v64, v66
	v_add_f32_e32 v7, v7, v52
	ds_bpermute_b32 v52, v2, v7
	s_waitcnt lgkmcnt(0)
	v_add_f32_e32 v7, v7, v52
	ds_bpermute_b32 v52, v11, v7
	s_waitcnt lgkmcnt(0)
	v_add_f32_e32 v7, v7, v52
	ds_bpermute_b32 v52, v12, v7
	s_waitcnt lgkmcnt(0)
	v_add_f32_e32 v7, v7, v52
	ds_bpermute_b32 v52, v13, v7
	s_waitcnt lgkmcnt(0)
	v_add_f32_e32 v7, v7, v52
	ds_bpermute_b32 v52, v14, v7
	s_waitcnt lgkmcnt(0)
	v_add_f32_e32 v7, v7, v52
	ds_bpermute_b32 v52, v15, v7
	s_and_saveexec_b64 s[6:7], s[0:1]
	s_cbranch_execz .LBB0_250
	s_waitcnt lgkmcnt(0)
	v_add_f32_e32 v7, v7, v52
	v_fmamk_f32 v7, v7, 0x3a000000, v214
	v_mul_f32_e32 v52, 0x4f800000, v7
	v_cmp_gt_f32_e32 vcc, s79, v7
	v_lshl_add_u64 v[8:9], v[8:9], 2, s[8:9]
	s_nop 0
	v_cndmask_b32_e32 v7, v7, v52, vcc
	v_sqrt_f32_e32 v52, v7
	s_nop 0
	v_add_u32_e32 v53, -1, v52
	v_fma_f32 v55, -v53, v52, v7
	v_add_u32_e32 v54, 1, v52
	v_cmp_ge_f32_e64 s[4:5], 0, v55
	s_nop 1
	v_cndmask_b32_e64 v53, v52, v53, s[4:5]
	v_fma_f32 v52, -v54, v52, v7
	v_cmp_lt_f32_e64 s[4:5], 0, v52
	s_nop 1
	v_cndmask_b32_e64 v52, v53, v54, s[4:5]
	v_mul_f32_e32 v53, 0x37800000, v52
	v_cndmask_b32_e32 v52, v52, v53, vcc
	v_cmp_class_f32_e32 vcc, v7, v1
	s_nop 1
	v_cndmask_b32_e32 v7, v52, v7, vcc
	v_div_scale_f32 v52, s[4:5], v7, v7, 1.0
	v_rcp_f32_e32 v53, v52
	s_nop 0
	v_fma_f32 v54, -v52, v53, 1.0
	v_fmac_f32_e32 v53, v54, v53
	v_div_scale_f32 v54, vcc, 1.0, v7, 1.0
	v_mul_f32_e32 v55, v54, v53
	v_fma_f32 v56, -v52, v55, v54
	v_fmac_f32_e32 v55, v56, v53
	v_fma_f32 v52, -v52, v55, v54
	v_div_fmas_f32 v52, v52, v53, v55
	v_div_fixup_f32 v7, v52, v7, 1.0
	flat_store_dword v[8:9], v7
.LBB0_250:
	s_or_b64 exec, exec, s[6:7]
	v_or_b32_e32 v6, 2, v6
	v_ashrrev_i32_e32 v7, 31, v6
	s_waitcnt lgkmcnt(0)
	s_movk_i32 s4, 0x1000
	s_nop 1
	v_mul_f32_e32 v8, v85, v85
	v_mul_f32_e32 v9, v87, v87
	v_mul_f32_e32 v85, v89, v89
	v_mul_f32_e32 v87, v91, v91
	v_mul_f32_e32 v89, v93, v93
	v_mul_f32_e32 v91, v95, v95
	v_fmac_f32_e32 v8, v84, v84
	v_fmac_f32_e32 v9, v86, v86
	v_fmac_f32_e32 v85, v88, v88
	v_fmac_f32_e32 v87, v90, v90
	v_mul_f32_e32 v93, v97, v97
	v_mul_f32_e32 v95, v99, v99
	v_fmac_f32_e32 v89, v92, v92
	v_fmac_f32_e32 v91, v94, v94
	v_add_f32_e32 v8, v8, v9
	v_add_f32_e32 v9, v85, v87
	v_fmac_f32_e32 v93, v96, v96
	v_fmac_f32_e32 v95, v98, v98
	v_mul_f32_e32 v84, v101, v101
	v_mul_f32_e32 v86, v103, v103
	v_add_f32_e32 v85, v89, v91
	v_add_f32_e32 v8, v8, v9
	v_mul_f32_e32 v88, v105, v105
	v_mul_f32_e32 v90, v107, v107
	v_add_f32_e32 v87, v93, v95
	v_fmac_f32_e32 v84, v100, v100
	v_fmac_f32_e32 v86, v102, v102
	v_add_f32_e32 v8, v8, v85
	v_mul_f32_e32 v92, v109, v109
	v_mul_f32_e32 v94, v111, v111
	v_fmac_f32_e32 v88, v104, v104
	v_fmac_f32_e32 v90, v106, v106
	v_add_f32_e32 v9, v84, v86
	v_add_f32_e32 v8, v8, v87
	v_mul_f32_e32 v96, v113, v113
	v_mul_f32_e32 v97, v115, v115
	v_fmac_f32_e32 v92, v108, v108
	v_fmac_f32_e32 v94, v110, v110
	v_add_f32_e32 v84, v88, v90
	v_add_f32_e32 v8, v8, v9
	v_fmac_f32_e32 v96, v112, v112
	v_fmac_f32_e32 v97, v114, v114
	v_add_f32_e32 v86, v92, v94
	v_add_f32_e32 v8, v8, v84
	v_add_f32_e32 v8, v8, v86
	v_add_f32_e32 v9, v96, v97
	v_add_f32_e32 v8, v8, v9
	ds_bpermute_b32 v9, v2, v8
	s_waitcnt lgkmcnt(0)
	v_add_f32_e32 v8, v8, v9
	ds_bpermute_b32 v9, v11, v8
	s_waitcnt lgkmcnt(0)
	v_add_f32_e32 v8, v8, v9
	ds_bpermute_b32 v9, v12, v8
	s_waitcnt lgkmcnt(0)
	v_add_f32_e32 v8, v8, v9
	ds_bpermute_b32 v9, v13, v8
	s_waitcnt lgkmcnt(0)
	v_add_f32_e32 v8, v8, v9
	ds_bpermute_b32 v9, v14, v8
	s_waitcnt lgkmcnt(0)
	v_add_f32_e32 v8, v8, v9
	ds_bpermute_b32 v9, v15, v8
	s_and_saveexec_b64 s[6:7], s[0:1]
	s_cbranch_execz .LBB0_252
	s_waitcnt lgkmcnt(0)
	v_add_f32_e32 v8, v8, v9
	v_fmamk_f32 v8, v8, 0x3a000000, v214
	v_mul_f32_e32 v9, 0x4f800000, v8
	v_cmp_gt_f32_e32 vcc, s79, v8
	v_lshl_add_u64 v[6:7], v[6:7], 2, s[8:9]
	s_nop 0
	v_cndmask_b32_e32 v8, v8, v9, vcc
	v_sqrt_f32_e32 v9, v8
	s_nop 0
	v_add_u32_e32 v84, -1, v9
	v_fma_f32 v86, -v84, v9, v8
	v_add_u32_e32 v85, 1, v9
	v_cmp_ge_f32_e64 s[4:5], 0, v86
	s_nop 1
	v_cndmask_b32_e64 v84, v9, v84, s[4:5]
	v_fma_f32 v9, -v85, v9, v8
	v_cmp_lt_f32_e64 s[4:5], 0, v9
	s_nop 1
	v_cndmask_b32_e64 v9, v84, v85, s[4:5]
	v_mul_f32_e32 v84, 0x37800000, v9
	v_cndmask_b32_e32 v9, v9, v84, vcc
	v_cmp_class_f32_e32 vcc, v8, v1
	s_nop 1
	v_cndmask_b32_e32 v8, v9, v8, vcc
	v_div_scale_f32 v9, s[4:5], v8, v8, 1.0
	v_rcp_f32_e32 v84, v9
	s_nop 0
	v_fma_f32 v85, -v9, v84, 1.0
	v_fmac_f32_e32 v84, v85, v84
	v_div_scale_f32 v85, vcc, 1.0, v8, 1.0
	v_mul_f32_e32 v86, v85, v84
	v_fma_f32 v87, -v9, v86, v85
	v_fmac_f32_e32 v86, v87, v84
	v_fma_f32 v9, -v9, v86, v85
	v_div_fmas_f32 v9, v9, v84, v86
	v_div_fixup_f32 v8, v9, v8, 1.0
	flat_store_dword v[6:7], v8
.LBB0_252:
	s_or_b64 exec, exec, s[6:7]
	v_or_b32_e32 v6, 3, v10
	v_ashrrev_i32_e32 v7, 31, v6
	s_waitcnt lgkmcnt(0)
	s_movk_i32 s4, 0x1000
	v_mul_f32_e32 v8, v121, v121
	v_mul_f32_e32 v4, v117, v117
	v_mul_f32_e32 v5, v119, v119
	v_mul_f32_e32 v9, v123, v123
	v_mul_f32_e32 v10, v125, v125
	v_mul_f32_e32 v117, v127, v127
	v_fmac_f32_e32 v4, v116, v116
	v_fmac_f32_e32 v5, v118, v118
	v_fmac_f32_e32 v8, v120, v120
	v_fmac_f32_e32 v9, v122, v122
	v_mul_f32_e32 v119, v129, v129
	v_mul_f32_e32 v121, v131, v131
	v_fmac_f32_e32 v10, v124, v124
	v_fmac_f32_e32 v117, v126, v126
	v_add_f32_e32 v4, v4, v5
	v_add_f32_e32 v5, v8, v9
	v_fmac_f32_e32 v119, v128, v128
	v_fmac_f32_e32 v121, v130, v130
	v_add_f32_e32 v8, v10, v117
	v_add_f32_e32 v4, v4, v5
	v_add_f32_e32 v9, v119, v121
	v_add_f32_e32 v4, v4, v8
	v_add_f32_e32 v4, v4, v9
	v_mul_f32_e32 v116, v133, v133
	v_mul_f32_e32 v118, v135, v135
	v_mul_f32_e32 v120, v137, v137
	v_mul_f32_e32 v122, v139, v139
	v_fmac_f32_e32 v116, v132, v132
	v_fmac_f32_e32 v118, v134, v134
	v_mul_f32_e32 v123, v141, v141
	v_mul_f32_e32 v124, v143, v143
	v_fmac_f32_e32 v120, v136, v136
	v_fmac_f32_e32 v122, v138, v138
	v_add_f32_e32 v5, v116, v118
	v_mul_f32_e32 v125, v145, v145
	v_mul_f32_e32 v126, v147, v147
	v_fmac_f32_e32 v123, v140, v140
	v_fmac_f32_e32 v124, v142, v142
	v_add_f32_e32 v10, v120, v122
	v_add_f32_e32 v4, v4, v5
	v_fmac_f32_e32 v125, v144, v144
	v_fmac_f32_e32 v126, v146, v146
	v_add_f32_e32 v116, v123, v124
	v_add_f32_e32 v4, v4, v10
	v_add_f32_e32 v4, v4, v116
	v_add_f32_e32 v5, v125, v126
	v_add_f32_e32 v4, v4, v5
	ds_bpermute_b32 v2, v2, v4
	s_waitcnt lgkmcnt(0)
	v_add_f32_e32 v2, v4, v2
	ds_bpermute_b32 v4, v11, v2
	s_waitcnt lgkmcnt(0)
	v_add_f32_e32 v2, v2, v4
	ds_bpermute_b32 v4, v12, v2
	s_waitcnt lgkmcnt(0)
	v_add_f32_e32 v2, v2, v4
	ds_bpermute_b32 v4, v13, v2
	s_waitcnt lgkmcnt(0)
	v_add_f32_e32 v2, v2, v4
	ds_bpermute_b32 v4, v14, v2
	s_waitcnt lgkmcnt(0)
	v_add_f32_e32 v2, v2, v4
	ds_bpermute_b32 v4, v15, v2
	s_and_saveexec_b64 s[4:5], s[0:1]
	s_cbranch_execz .LBB0_254
	s_waitcnt lgkmcnt(0)
	v_add_f32_e32 v2, v2, v4
	v_fmamk_f32 v2, v2, 0x3a000000, v214
	v_mul_f32_e32 v4, 0x4f800000, v2
	v_cmp_gt_f32_e32 vcc, s79, v2
	s_nop 1
	v_cndmask_b32_e32 v2, v2, v4, vcc
	v_sqrt_f32_e32 v4, v2
	s_nop 0
	v_add_u32_e32 v5, -1, v4
	v_fma_f32 v9, -v5, v4, v2
	v_add_u32_e32 v8, 1, v4
	v_cmp_ge_f32_e64 s[0:1], 0, v9
	s_nop 1
	v_cndmask_b32_e64 v5, v4, v5, s[0:1]
	v_fma_f32 v4, -v8, v4, v2
	v_cmp_lt_f32_e64 s[0:1], 0, v4
	s_nop 1
	v_cndmask_b32_e64 v4, v5, v8, s[0:1]
	v_mul_f32_e32 v5, 0x37800000, v4
	v_cndmask_b32_e32 v4, v4, v5, vcc
	v_cmp_class_f32_e32 vcc, v2, v1
	s_nop 1
	v_cndmask_b32_e32 v2, v4, v2, vcc
	v_div_scale_f32 v4, s[0:1], v2, v2, 1.0
	v_rcp_f32_e32 v5, v4
	s_nop 0
	v_fma_f32 v8, -v4, v5, 1.0
	v_fmac_f32_e32 v5, v8, v5
	v_div_scale_f32 v8, vcc, 1.0, v2, 1.0
	v_mul_f32_e32 v9, v8, v5
	v_fma_f32 v10, -v4, v9, v8
	v_fmac_f32_e32 v9, v10, v5
	v_fma_f32 v4, -v4, v9, v8
	v_div_fmas_f32 v4, v4, v5, v9
	v_div_fixup_f32 v2, v4, v2, 1.0
	v_lshl_add_u64 v[4:5], v[6:7], 2, s[8:9]
	flat_store_dword v[4:5], v2

.LBB0_1595:
	v_readlane_b32 s0, v255, 0
	s_cmp_eq_u32 s0, 3
	s_cbranch_scc1 .LBB0_1638
	v_readlane_b32 s20, v253, 4
	v_readlane_b32 s21, v253, 5
	v_readlane_b32 s36, v253, 6
	s_waitcnt vmcnt(0)
	s_waitcnt lgkmcnt(0)
	s_barrier
	s_mov_b64 s[2:3], exec
	v_readlane_b32 s0, v253, 7
	v_readlane_b32 s1, v253, 8
	s_and_b64 s[0:1], s[2:3], s[0:1]
	s_mov_b64 exec, s[0:1]
	s_cbranch_execnz .LBB0_1596
	s_getpc_b64 s[98:99]
